# grid barrier: last XCD leader bumps every XCD release word directly (one hop less per barrier)
# speedup vs baseline: 1.0182x; 1.0016x over previous
; __device__ __forceinline__ unsigned xb_ld(unsigned* p)              { return __hip_atomic_load(p, __ATOMIC_RELAXED, __HIP_MEMORY_SCOPE_AGENT); }
; __device__ __forceinline__ unsigned xb_add(unsigned* p, unsigned v) { return __hip_atomic_fetch_add(p, v, __ATOMIC_RELAXED, __HIP_MEMORY_SCOPE_AGENT); }
; #define XB_SPIN(cond, bar) do { unsigned _sp = 0; while (cond) { __builtin_amdgcn_s_sleep(1); \
;     if ((++_sp & 255u) == 0u) { if (xb_ld(&(bar)[XB_TMO])) break; if (_sp > XB_SPIN_CAP) { atomicAdd(&(bar)[XB_TMO], 1u); break; } } } } while (0)
; __device__ __forceinline__ void xcd_barrier(const XcdBarrier& b) {
;     ...
;         const unsigned old = xb_add(&bar[XB_XSUB(b.x)], 1u);
;         const unsigned gen = old / nloc;
;         if (old + 1u == (gen + 1u) * nloc) {
;             __builtin_amdgcn_fence(__ATOMIC_RELEASE, "agent");
;             asm volatile("s_waitcnt vmcnt(0)" ::: "memory");
;             const unsigned og = xb_add(&bar[XB_TOP], 1u);
;             const unsigned tg = og / nx;
;             if (og + 1u == (tg + 1u) * nx) xb_add(&bar[XB_TOPGEN], 1u);
;             else XB_SPIN(xb_ld(&bar[XB_TOPGEN]) == tg, bar);
;             __builtin_amdgcn_fence(__ATOMIC_ACQUIRE, "agent");
;             xb_add(&bar[XB_XGEN(b.x)], 1u);
;             asm volatile("s_waitcnt vmcnt(0)" ::: "memory");
;         } else {
;             XB_SPIN(xb_ld(&bar[XB_XGEN(b.x)]) == gen, bar);
.LBB0_112:
	s_or_b64 exec, exec, s[10:11]
	v_cvt_f32_u32_e32 v4, v1
	s_waitcnt vmcnt(0)
	v_readfirstlane_b32 s8, v3
	s_add_u32 s10, s6, 0x2400
	s_addc_u32 s11, s7, 0
	v_rcp_iflag_f32_e32 v4, v4
	v_add_u32_e32 v2, s8, v2
	v_add_u32_e32 v5, 1, v2
	s_mov_b64 s[12:13], 0
	v_mul_f32_e32 v3, 0x4f7ffffe, v4
	v_cvt_u32_f32_e32 v3, v3
	v_sub_u32_e32 v4, 0, v1
	v_mul_lo_u32 v4, v4, v3
	v_mul_hi_u32 v4, v3, v4
	v_add_u32_e32 v3, v3, v4
	v_mul_hi_u32 v3, v2, v3
	v_mul_lo_u32 v4, v3, v1
	v_sub_u32_e32 v2, v2, v4
	v_add_u32_e32 v6, 1, v3
	v_cmp_ge_u32_e32 vcc, v2, v1
	v_sub_u32_e32 v4, v2, v1
	s_nop 0
	v_cndmask_b32_e32 v3, v3, v6, vcc
	v_cndmask_b32_e32 v2, v2, v4, vcc
	v_add_u32_e32 v4, 1, v3
	v_cmp_ge_u32_e32 vcc, v2, v1
	s_nop 1
	v_cndmask_b32_e32 v4, v3, v4, vcc
	v_mul_lo_u32 v2, v1, v4
	v_add_u32_e32 v1, v2, v1
	v_cmp_ne_u32_e32 vcc, v5, v1
	s_cbranch_vccnz .Lxb_notlast_0
	v_mov_b32_e32 v2, 0x6400
	v_mov_b32_e32 v3, 1
	global_atomic_add v2, v3, s[84:85] offset:0
	global_atomic_add v2, v3, s[84:85] offset:256
	global_atomic_add v2, v3, s[84:85] offset:512
	global_atomic_add v2, v3, s[84:85] offset:768
	global_atomic_add v2, v3, s[84:85] offset:1024
	global_atomic_add v2, v3, s[84:85] offset:1280
	global_atomic_add v2, v3, s[84:85] offset:1536
	global_atomic_add v2, v3, s[84:85] offset:1792
	global_atomic_add v2, v3, s[84:85] offset:2048
	global_atomic_add v2, v3, s[84:85] offset:2304
	global_atomic_add v2, v3, s[84:85] offset:2560
	global_atomic_add v2, v3, s[84:85] offset:2816
	global_atomic_add v2, v3, s[84:85] offset:3072
	global_atomic_add v2, v3, s[84:85] offset:3328
	global_atomic_add v2, v3, s[84:85] offset:3584
	global_atomic_add v2, v3, s[84:85] offset:3840
.Lxb_notlast_0:
	v_mov_b64_e32 v[2:3], s[10:11]
	s_and_saveexec_b64 s[8:9], vcc
	s_cbranch_execz .LBB0_124
	v_mov_b32_e32 v1, 0
	global_load_dword v2, v1, s[10:11] sc1
	s_mov_b64 s[26:27], 0
	s_waitcnt vmcnt(0)
	v_cmp_eq_u32_e32 vcc, v2, v4
	s_and_saveexec_b64 s[24:25], vcc
	s_cbranch_execz .LBB0_123
	s_add_u32 s12, s84, 0x4200
	s_addc_u32 s13, s85, 0
	s_mov_b32 s33, 1
	s_branch .LBB0_116

; __device__ __forceinline__ unsigned xb_add(unsigned* p, unsigned v) { return __hip_atomic_fetch_add(p, v, __ATOMIC_RELAXED, __HIP_MEMORY_SCOPE_AGENT); }
; __device__ __forceinline__ void xcd_barrier(const XcdBarrier& b) {
;     ...
;             __builtin_amdgcn_fence(__ATOMIC_ACQUIRE, "agent");
;             xb_add(&bar[XB_XGEN(b.x)], 1u);
;             asm volatile("s_waitcnt vmcnt(0)" ::: "memory");
.LBB0_126:
	s_or_b64 exec, exec, s[8:9]
	v_mov_b32_e32 v1, 0x2000
	v_mov_b32_e32 v2, 1
	s_waitcnt vmcnt(0)
	s_waitcnt vmcnt(0)

; __device__ __forceinline__ unsigned xb_ld(unsigned* p)              { return __hip_atomic_load(p, __ATOMIC_RELAXED, __HIP_MEMORY_SCOPE_AGENT); }
; __device__ __forceinline__ unsigned xb_add(unsigned* p, unsigned v) { return __hip_atomic_fetch_add(p, v, __ATOMIC_RELAXED, __HIP_MEMORY_SCOPE_AGENT); }
; #define XB_SPIN(cond, bar) do { unsigned _sp = 0; while (cond) { __builtin_amdgcn_s_sleep(1); \
;     if ((++_sp & 255u) == 0u) { if (xb_ld(&(bar)[XB_TMO])) break; if (_sp > XB_SPIN_CAP) { atomicAdd(&(bar)[XB_TMO], 1u); break; } } } } while (0)
; __device__ __forceinline__ void xcd_barrier(const XcdBarrier& b) {
;     ...
;         const unsigned old = xb_add(&bar[XB_XSUB(b.x)], 1u);
;         const unsigned gen = old / nloc;
;         if (old + 1u == (gen + 1u) * nloc) {
;             __builtin_amdgcn_fence(__ATOMIC_RELEASE, "agent");
;             asm volatile("s_waitcnt vmcnt(0)" ::: "memory");
;             const unsigned og = xb_add(&bar[XB_TOP], 1u);
;             const unsigned tg = og / nx;
;             if (og + 1u == (tg + 1u) * nx) xb_add(&bar[XB_TOPGEN], 1u);
;             else XB_SPIN(xb_ld(&bar[XB_TOPGEN]) == tg, bar);
;             __builtin_amdgcn_fence(__ATOMIC_ACQUIRE, "agent");
;             xb_add(&bar[XB_XGEN(b.x)], 1u);
;             asm volatile("s_waitcnt vmcnt(0)" ::: "memory");
;         } else {
;             XB_SPIN(xb_ld(&bar[XB_XGEN(b.x)]) == gen, bar);
.LBB0_196:
	s_or_b64 exec, exec, s[8:9]
	v_cvt_f32_u32_e32 v4, v1
	s_waitcnt vmcnt(0)
	v_readfirstlane_b32 s6, v3
	s_add_u32 s8, s4, 0x2400
	s_addc_u32 s9, s5, 0
	v_rcp_iflag_f32_e32 v4, v4
	v_add_u32_e32 v2, s6, v2
	v_add_u32_e32 v5, 1, v2
	s_mov_b64 s[10:11], 0
	v_mul_f32_e32 v3, 0x4f7ffffe, v4
	v_cvt_u32_f32_e32 v3, v3
	v_sub_u32_e32 v4, 0, v1
	v_mul_lo_u32 v4, v4, v3
	v_mul_hi_u32 v4, v3, v4
	v_add_u32_e32 v3, v3, v4
	v_mul_hi_u32 v3, v2, v3
	v_mul_lo_u32 v4, v3, v1
	v_sub_u32_e32 v2, v2, v4
	v_add_u32_e32 v6, 1, v3
	v_cmp_ge_u32_e32 vcc, v2, v1
	v_sub_u32_e32 v4, v2, v1
	s_nop 0
	v_cndmask_b32_e32 v3, v3, v6, vcc
	v_cndmask_b32_e32 v2, v2, v4, vcc
	v_add_u32_e32 v4, 1, v3
	v_cmp_ge_u32_e32 vcc, v2, v1
	s_nop 1
	v_cndmask_b32_e32 v4, v3, v4, vcc
	v_mul_lo_u32 v2, v1, v4
	v_add_u32_e32 v1, v2, v1
	v_cmp_ne_u32_e32 vcc, v5, v1
	s_cbranch_vccnz .Lxb_notlast_1
	v_mov_b32_e32 v2, 0x6400
	v_mov_b32_e32 v3, 1
	global_atomic_add v2, v3, s[84:85] offset:0
	global_atomic_add v2, v3, s[84:85] offset:256
	global_atomic_add v2, v3, s[84:85] offset:512
	global_atomic_add v2, v3, s[84:85] offset:768
	global_atomic_add v2, v3, s[84:85] offset:1024
	global_atomic_add v2, v3, s[84:85] offset:1280
	global_atomic_add v2, v3, s[84:85] offset:1536
	global_atomic_add v2, v3, s[84:85] offset:1792
	global_atomic_add v2, v3, s[84:85] offset:2048
	global_atomic_add v2, v3, s[84:85] offset:2304
	global_atomic_add v2, v3, s[84:85] offset:2560
	global_atomic_add v2, v3, s[84:85] offset:2816
	global_atomic_add v2, v3, s[84:85] offset:3072
	global_atomic_add v2, v3, s[84:85] offset:3328
	global_atomic_add v2, v3, s[84:85] offset:3584
	global_atomic_add v2, v3, s[84:85] offset:3840
.Lxb_notlast_1:
	v_mov_b64_e32 v[2:3], s[8:9]
	s_and_saveexec_b64 s[6:7], vcc
	s_cbranch_execz .LBB0_208
	v_mov_b32_e32 v1, 0
	global_load_dword v2, v1, s[8:9] sc1
	s_mov_b64 s[14:15], 0
	s_waitcnt vmcnt(0)
	v_cmp_eq_u32_e32 vcc, v2, v4
	s_and_saveexec_b64 s[12:13], vcc
	s_cbranch_execz .LBB0_207
	s_add_u32 s10, s84, 0x4200
	s_addc_u32 s11, s85, 0
	s_mov_b32 s28, 1
	s_branch .LBB0_200

; __device__ __forceinline__ unsigned xb_add(unsigned* p, unsigned v) { return __hip_atomic_fetch_add(p, v, __ATOMIC_RELAXED, __HIP_MEMORY_SCOPE_AGENT); }
; __device__ __forceinline__ void xcd_barrier(const XcdBarrier& b) {
;     ...
;             __builtin_amdgcn_fence(__ATOMIC_ACQUIRE, "agent");
;             xb_add(&bar[XB_XGEN(b.x)], 1u);
;             asm volatile("s_waitcnt vmcnt(0)" ::: "memory");
.LBB0_210:
	s_or_b64 exec, exec, s[6:7]
	v_mov_b32_e32 v1, 0x2000
	v_mov_b32_e32 v2, 1
	s_waitcnt vmcnt(0)
	s_waitcnt vmcnt(0)

; __device__ __forceinline__ unsigned xb_ld(unsigned* p)              { return __hip_atomic_load(p, __ATOMIC_RELAXED, __HIP_MEMORY_SCOPE_AGENT); }
; __device__ __forceinline__ unsigned xb_add(unsigned* p, unsigned v) { return __hip_atomic_fetch_add(p, v, __ATOMIC_RELAXED, __HIP_MEMORY_SCOPE_AGENT); }
; #define XB_SPIN(cond, bar) do { unsigned _sp = 0; while (cond) { __builtin_amdgcn_s_sleep(1); \
;     if ((++_sp & 255u) == 0u) { if (xb_ld(&(bar)[XB_TMO])) break; if (_sp > XB_SPIN_CAP) { atomicAdd(&(bar)[XB_TMO], 1u); break; } } } } while (0)
; __device__ __forceinline__ void xcd_barrier(const XcdBarrier& b) {
;     ...
;         if (old + 1u == (gen + 1u) * nloc) {
;             __builtin_amdgcn_fence(__ATOMIC_RELEASE, "agent");
;             asm volatile("s_waitcnt vmcnt(0)" ::: "memory");
;             const unsigned og = xb_add(&bar[XB_TOP], 1u);
;             const unsigned tg = og / nx;
;             if (og + 1u == (tg + 1u) * nx) xb_add(&bar[XB_TOPGEN], 1u);
;             else XB_SPIN(xb_ld(&bar[XB_TOPGEN]) == tg, bar);
;             __builtin_amdgcn_fence(__ATOMIC_ACQUIRE, "agent");
;             xb_add(&bar[XB_XGEN(b.x)], 1u);
;             asm volatile("s_waitcnt vmcnt(0)" ::: "memory");
;         } else {
;             XB_SPIN(xb_ld(&bar[XB_XGEN(b.x)]) == gen, bar);
.Lxb_notlast_2:
	v_mov_b64_e32 v[2:3], s[8:9]
	s_and_saveexec_b64 s[6:7], vcc
	s_cbranch_execz .LBB0_614
	v_mov_b32_e32 v1, 0
	global_load_dword v2, v1, s[8:9] sc1
	s_mov_b64 s[14:15], 0
	s_waitcnt vmcnt(0)
	v_cmp_eq_u32_e32 vcc, v2, v4
	s_and_saveexec_b64 s[12:13], vcc
	s_cbranch_execz .LBB0_613
	s_add_u32 s10, s84, 0x4200
	s_addc_u32 s11, s85, 0
	s_mov_b32 s24, 1
	s_branch .LBB0_606

; __device__ __forceinline__ unsigned xb_ld(unsigned* p)              { return __hip_atomic_load(p, __ATOMIC_RELAXED, __HIP_MEMORY_SCOPE_AGENT); }
; __device__ __forceinline__ unsigned xb_add(unsigned* p, unsigned v) { return __hip_atomic_fetch_add(p, v, __ATOMIC_RELAXED, __HIP_MEMORY_SCOPE_AGENT); }
; #define XB_SPIN(cond, bar) do { unsigned _sp = 0; while (cond) { __builtin_amdgcn_s_sleep(1); \
;     if ((++_sp & 255u) == 0u) { if (xb_ld(&(bar)[XB_TMO])) break; if (_sp > XB_SPIN_CAP) { atomicAdd(&(bar)[XB_TMO], 1u); break; } } } } while (0)
; __device__ __forceinline__ void xcd_barrier(const XcdBarrier& b) {
;     ...
;         const unsigned old = xb_add(&bar[XB_XSUB(b.x)], 1u);
;         const unsigned gen = old / nloc;
;         if (old + 1u == (gen + 1u) * nloc) {
;             __builtin_amdgcn_fence(__ATOMIC_RELEASE, "agent");
;             asm volatile("s_waitcnt vmcnt(0)" ::: "memory");
;             const unsigned og = xb_add(&bar[XB_TOP], 1u);
;             const unsigned tg = og / nx;
;             if (og + 1u == (tg + 1u) * nx) xb_add(&bar[XB_TOPGEN], 1u);
;             else XB_SPIN(xb_ld(&bar[XB_TOPGEN]) == tg, bar);
;             __builtin_amdgcn_fence(__ATOMIC_ACQUIRE, "agent");
;             xb_add(&bar[XB_XGEN(b.x)], 1u);
;             asm volatile("s_waitcnt vmcnt(0)" ::: "memory");
;         } else {
;             XB_SPIN(xb_ld(&bar[XB_XGEN(b.x)]) == gen, bar);
.LBB0_1243:
	s_or_b64 exec, exec, s[8:9]
	v_cvt_f32_u32_e32 v5, v2
	s_waitcnt vmcnt(0)
	v_readfirstlane_b32 s6, v4
	s_add_u32 s8, s4, 0x2400
	s_addc_u32 s9, s5, 0
	v_rcp_iflag_f32_e32 v5, v5
	v_add_u32_e32 v3, s6, v3
	v_add_u32_e32 v6, 1, v3
	s_mov_b64 s[10:11], 0
	v_mul_f32_e32 v4, 0x4f7ffffe, v5
	v_cvt_u32_f32_e32 v4, v4
	v_sub_u32_e32 v5, 0, v2
	v_mul_lo_u32 v5, v5, v4
	v_mul_hi_u32 v5, v4, v5
	v_add_u32_e32 v4, v4, v5
	v_mul_hi_u32 v4, v3, v4
	v_mul_lo_u32 v5, v4, v2
	v_sub_u32_e32 v3, v3, v5
	v_add_u32_e32 v7, 1, v4
	v_cmp_ge_u32_e32 vcc, v3, v2
	v_sub_u32_e32 v5, v3, v2
	s_nop 0
	v_cndmask_b32_e32 v4, v4, v7, vcc
	v_cndmask_b32_e32 v3, v3, v5, vcc
	v_add_u32_e32 v5, 1, v4
	v_cmp_ge_u32_e32 vcc, v3, v2
	s_nop 1
	v_cndmask_b32_e32 v4, v4, v5, vcc
	v_mul_lo_u32 v3, v2, v4
	v_add_u32_e32 v2, v3, v2
	v_cmp_ne_u32_e32 vcc, v6, v2
	s_cbranch_vccnz .Lxb_notlast_6
	v_mov_b32_e32 v2, 0x6400
	v_mov_b32_e32 v3, 1
	global_atomic_add v2, v3, s[84:85] offset:0
	global_atomic_add v2, v3, s[84:85] offset:256
	global_atomic_add v2, v3, s[84:85] offset:512
	global_atomic_add v2, v3, s[84:85] offset:768
	global_atomic_add v2, v3, s[84:85] offset:1024
	global_atomic_add v2, v3, s[84:85] offset:1280
	global_atomic_add v2, v3, s[84:85] offset:1536
	global_atomic_add v2, v3, s[84:85] offset:1792
	global_atomic_add v2, v3, s[84:85] offset:2048
	global_atomic_add v2, v3, s[84:85] offset:2304
	global_atomic_add v2, v3, s[84:85] offset:2560
	global_atomic_add v2, v3, s[84:85] offset:2816
	global_atomic_add v2, v3, s[84:85] offset:3072
	global_atomic_add v2, v3, s[84:85] offset:3328
	global_atomic_add v2, v3, s[84:85] offset:3584
	global_atomic_add v2, v3, s[84:85] offset:3840
.Lxb_notlast_6:
	v_mov_b64_e32 v[2:3], s[8:9]
	s_and_saveexec_b64 s[6:7], vcc
	s_cbranch_execz .LBB0_1255
	v_mov_b32_e32 v2, 0
	global_load_dword v3, v2, s[8:9] sc1
	s_mov_b64 s[14:15], 0
	s_waitcnt vmcnt(0)
	v_cmp_eq_u32_e32 vcc, v3, v4
	s_and_saveexec_b64 s[12:13], vcc
	s_cbranch_execz .LBB0_1254
	s_add_u32 s10, s84, 0x4200
	s_addc_u32 s11, s85, 0
	s_mov_b32 s24, 1
	s_branch .LBB0_1247

; __device__ __forceinline__ unsigned xb_add(unsigned* p, unsigned v) { return __hip_atomic_fetch_add(p, v, __ATOMIC_RELAXED, __HIP_MEMORY_SCOPE_AGENT); }
; __device__ __forceinline__ void xcd_barrier(const XcdBarrier& b) {
;     ...
;             __builtin_amdgcn_fence(__ATOMIC_ACQUIRE, "agent");
;             xb_add(&bar[XB_XGEN(b.x)], 1u);
;             asm volatile("s_waitcnt vmcnt(0)" ::: "memory");
.LBB0_1257:
	s_or_b64 exec, exec, s[6:7]
	v_mov_b32_e32 v2, 0x2000
	v_mov_b32_e32 v3, 1
	s_waitcnt vmcnt(0)
	s_waitcnt vmcnt(0)
